# G3 epilogue rewritten by hand: relu, packed f32 square, bf16 pack, one running row pointer (no canonicalising max, no per-row address rebuild); spill-lane restores of s[68:69] kept
# baseline (speedup 1.0000x reference)
; __device__ __forceinline__ unsigned cvt_pk_bf16(float lo, float hi) { unsigned r; asm volatile("v_cvt_pk_bf16_f32 %0, %1, %2" : "=v"(r) : "v"(lo), "v"(hi)); return r; }
;     __device__ __forceinline__ void operator()(const f32x4 (&acc)[2][2][4][2], const Unit& u, int wr, int wc, int fr, int fq) const {
;         const int row0 = u.pm * BM + wr * 64 + fr, col0 = u.pn * BM + wc * 32 + 8 * fq;
; #pragma unroll
;         for (int ai = 0; ai < 2; ++ai)
; #pragma unroll
;             for (int m = 0; m < 4; ++m) {
;                 bf16_t* rowp = H + (size_t)(row0 + ai * HALF + m * 16) * 4096 + col0;
; #pragma unroll
;                 for (int bj = 0; bj < 2; ++bj) {
;                     f32x4 v0 = acc[ai][bj][m][0], v1 = acc[ai][bj][m][1];
; #pragma unroll
;                     for (int i = 0; i < 4; ++i) { const float a = fmaxf(v0[i], 0.f), b = fmaxf(v1[i], 0.f); v0[i] = a * a; v1[i] = b * b; }
;                     u32x4 w; w.x = cvt_pk_bf16(v0[0], v0[1]); w.y = cvt_pk_bf16(v0[2], v0[3]); w.z = cvt_pk_bf16(v1[0], v1[1]); w.w = cvt_pk_bf16(v1[2], v1[3]);
;                     *(u32x4*)(rowp + bj * HALF) = w;
;                 }
.LBB0_909:
	v_lshl_add_u32 v144, s60, 8, v140
	v_lshl_or_b32 v138, s52, 8, v142
	v_ashrrev_i32_e32 v145, 31, v144
	v_ashrrev_i32_e32 v139, 31, v138
	v_lshlrev_b64 v[146:147], 13, v[144:145]
	s_mov_b64 s[12:13], 0x20000
	s_mov_b64 s[14:15], 0xa0000
	v_lshl_add_u64 v[146:147], s[0:1], 0, v[146:147]
	v_lshl_add_u64 v[146:147], v[138:139], 1, v[146:147]
	v_max_f32_e32 v120, 0, v120
	v_max_f32_e32 v121, 0, v121
	v_max_f32_e32 v122, 0, v122
	v_max_f32_e32 v123, 0, v123
	v_max_f32_e32 v124, 0, v124
	v_max_f32_e32 v125, 0, v125
	v_max_f32_e32 v126, 0, v126
	v_max_f32_e32 v127, 0, v127
	v_pk_mul_f32 v[120:121], v[120:121], v[120:121]
	v_pk_mul_f32 v[122:123], v[122:123], v[122:123]
	v_pk_mul_f32 v[124:125], v[124:125], v[124:125]
	v_pk_mul_f32 v[126:127], v[126:127], v[126:127]
	v_cvt_pk_bf16_f32 v124, v124, v125
	v_cvt_pk_bf16_f32 v125, v126, v127
	v_cvt_pk_bf16_f32 v126, v120, v121
	v_cvt_pk_bf16_f32 v127, v122, v123
	global_store_dwordx4 v[146:147], v[124:127], off
	v_max_f32_e32 v112, 0, v112
	v_max_f32_e32 v113, 0, v113
	v_max_f32_e32 v114, 0, v114
	v_max_f32_e32 v115, 0, v115
	v_max_f32_e32 v116, 0, v116
	v_max_f32_e32 v117, 0, v117
	v_max_f32_e32 v118, 0, v118
	v_max_f32_e32 v119, 0, v119
	v_pk_mul_f32 v[112:113], v[112:113], v[112:113]
	v_pk_mul_f32 v[114:115], v[114:115], v[114:115]
	v_pk_mul_f32 v[116:117], v[116:117], v[116:117]
	v_pk_mul_f32 v[118:119], v[118:119], v[118:119]
	v_cvt_pk_bf16_f32 v116, v116, v117
	v_cvt_pk_bf16_f32 v117, v118, v119
	v_cvt_pk_bf16_f32 v118, v112, v113
	v_cvt_pk_bf16_f32 v119, v114, v115
	global_store_dwordx4 v[146:147], v[116:119], off offset:256
	v_lshl_add_u64 v[146:147], v[146:147], 0, s[12:13]
	v_max_f32_e32 v104, 0, v104
	v_max_f32_e32 v105, 0, v105
	v_max_f32_e32 v106, 0, v106
	v_max_f32_e32 v107, 0, v107
	v_max_f32_e32 v108, 0, v108
	v_max_f32_e32 v109, 0, v109
	v_max_f32_e32 v110, 0, v110
	v_max_f32_e32 v111, 0, v111
	v_pk_mul_f32 v[104:105], v[104:105], v[104:105]
	v_pk_mul_f32 v[106:107], v[106:107], v[106:107]
	v_pk_mul_f32 v[108:109], v[108:109], v[108:109]
	v_pk_mul_f32 v[110:111], v[110:111], v[110:111]
	v_cvt_pk_bf16_f32 v108, v108, v109
	v_cvt_pk_bf16_f32 v109, v110, v111
	v_cvt_pk_bf16_f32 v110, v104, v105
	v_cvt_pk_bf16_f32 v111, v106, v107
	global_store_dwordx4 v[146:147], v[108:111], off
	v_max_f32_e32 v96, 0, v96
	v_max_f32_e32 v97, 0, v97
	v_max_f32_e32 v98, 0, v98
	v_max_f32_e32 v99, 0, v99
	v_max_f32_e32 v100, 0, v100
	v_max_f32_e32 v101, 0, v101
	v_max_f32_e32 v102, 0, v102
	v_max_f32_e32 v103, 0, v103
	v_pk_mul_f32 v[96:97], v[96:97], v[96:97]
	v_pk_mul_f32 v[98:99], v[98:99], v[98:99]
	v_pk_mul_f32 v[100:101], v[100:101], v[100:101]
	v_pk_mul_f32 v[102:103], v[102:103], v[102:103]
	v_cvt_pk_bf16_f32 v100, v100, v101
	v_cvt_pk_bf16_f32 v101, v102, v103
	v_cvt_pk_bf16_f32 v102, v96, v97
	v_cvt_pk_bf16_f32 v103, v98, v99
	global_store_dwordx4 v[146:147], v[100:103], off offset:256
	v_lshl_add_u64 v[146:147], v[146:147], 0, s[12:13]
	v_max_f32_e32 v88, 0, v88
	v_max_f32_e32 v89, 0, v89
	v_max_f32_e32 v90, 0, v90
	v_max_f32_e32 v91, 0, v91
	v_max_f32_e32 v92, 0, v92
	v_max_f32_e32 v93, 0, v93
	v_max_f32_e32 v94, 0, v94
	v_max_f32_e32 v95, 0, v95
	v_pk_mul_f32 v[88:89], v[88:89], v[88:89]
	v_pk_mul_f32 v[90:91], v[90:91], v[90:91]
	v_pk_mul_f32 v[92:93], v[92:93], v[92:93]
	v_pk_mul_f32 v[94:95], v[94:95], v[94:95]
	v_cvt_pk_bf16_f32 v92, v92, v93
	v_cvt_pk_bf16_f32 v93, v94, v95
	v_cvt_pk_bf16_f32 v94, v88, v89
	v_cvt_pk_bf16_f32 v95, v90, v91
	global_store_dwordx4 v[146:147], v[92:95], off
	v_max_f32_e32 v80, 0, v80
	v_max_f32_e32 v81, 0, v81
	v_max_f32_e32 v82, 0, v82
	v_max_f32_e32 v83, 0, v83
	v_max_f32_e32 v84, 0, v84
	v_max_f32_e32 v85, 0, v85
	v_max_f32_e32 v86, 0, v86
	v_max_f32_e32 v87, 0, v87
	v_pk_mul_f32 v[80:81], v[80:81], v[80:81]
	v_pk_mul_f32 v[82:83], v[82:83], v[82:83]
	v_pk_mul_f32 v[84:85], v[84:85], v[84:85]
	v_pk_mul_f32 v[86:87], v[86:87], v[86:87]
	v_cvt_pk_bf16_f32 v84, v84, v85
	v_cvt_pk_bf16_f32 v85, v86, v87
	v_cvt_pk_bf16_f32 v86, v80, v81
	v_cvt_pk_bf16_f32 v87, v82, v83
	global_store_dwordx4 v[146:147], v[84:87], off offset:256
	v_lshl_add_u64 v[146:147], v[146:147], 0, s[12:13]
	v_max_f32_e32 v72, 0, v72
	v_max_f32_e32 v73, 0, v73
	v_max_f32_e32 v74, 0, v74
	v_max_f32_e32 v75, 0, v75
	v_max_f32_e32 v76, 0, v76
	v_max_f32_e32 v77, 0, v77
	v_max_f32_e32 v78, 0, v78
	v_max_f32_e32 v79, 0, v79
	v_pk_mul_f32 v[72:73], v[72:73], v[72:73]
	v_pk_mul_f32 v[74:75], v[74:75], v[74:75]
	v_pk_mul_f32 v[76:77], v[76:77], v[76:77]
	v_pk_mul_f32 v[78:79], v[78:79], v[78:79]
	v_cvt_pk_bf16_f32 v76, v76, v77
	v_cvt_pk_bf16_f32 v77, v78, v79
	v_cvt_pk_bf16_f32 v78, v72, v73
	v_cvt_pk_bf16_f32 v79, v74, v75
	global_store_dwordx4 v[146:147], v[76:79], off
	v_max_f32_e32 v64, 0, v64
	v_max_f32_e32 v65, 0, v65
	v_max_f32_e32 v66, 0, v66
	v_max_f32_e32 v67, 0, v67
	v_max_f32_e32 v68, 0, v68
	v_max_f32_e32 v69, 0, v69
	v_max_f32_e32 v70, 0, v70
	v_max_f32_e32 v71, 0, v71
	v_pk_mul_f32 v[64:65], v[64:65], v[64:65]
	v_pk_mul_f32 v[66:67], v[66:67], v[66:67]
	v_pk_mul_f32 v[68:69], v[68:69], v[68:69]
	v_pk_mul_f32 v[70:71], v[70:71], v[70:71]
	v_cvt_pk_bf16_f32 v68, v68, v69
; __device__ __forceinline__ unsigned cvt_pk_bf16(float lo, float hi) { unsigned r; asm volatile("v_cvt_pk_bf16_f32 %0, %1, %2" : "=v"(r) : "v"(lo), "v"(hi)); return r; }
; #define PG8_BAR __builtin_amdgcn_s_barrier()
;     __device__ __forceinline__ void operator()(const f32x4 (&acc)[2][2][4][2], const Unit& u, int wr, int wc, int fr, int fq) const {
;     ...
;                 for (int bj = 0; bj < 2; ++bj) {
;                     f32x4 v0 = acc[ai][bj][m][0], v1 = acc[ai][bj][m][1];
; #pragma unroll
;                     for (int i = 0; i < 4; ++i) { const float a = fmaxf(v0[i], 0.f), b = fmaxf(v1[i], 0.f); v0[i] = a * a; v1[i] = b * b; }
;                     u32x4 w; w.x = cvt_pk_bf16(v0[0], v0[1]); w.y = cvt_pk_bf16(v0[2], v0[3]); w.z = cvt_pk_bf16(v1[0], v1[1]); w.w = cvt_pk_bf16(v1[2], v1[3]);
;                     *(u32x4*)(rowp + bj * HALF) = w;
;                 }
; template <class Epi, class Sched, bool ALIGN_EPI = false, bool SP2 = false>
; __device__ __forceinline__ void gemm_phase(PG8_LAS unsigned char* lds, const Gemm g, const Sched& S, const Epi& E) {
;     ...
;         if (!has_next) break;
; #pragma unroll
;         for (int a = 0; a < 2; ++a)
; #pragma unroll
;             for (int b = 0; b < 2; ++b)
; #pragma unroll
;                 for (int m = 0; m < 4; ++m)
; #pragma unroll
;                     for (int n = 0; n < 2; ++n) acc[a][b][m][n] = (f32x4){0.f, 0.f, 0.f, 0.f};
;         cur = nxt; cA = nA; cB = nB; ++ui;
;         if constexpr (ALIGN_EPI) { if (wr == 1) PG8_BAR; }
	v_cvt_pk_bf16_f32 v69, v70, v71
	v_cvt_pk_bf16_f32 v70, v64, v65
	v_cvt_pk_bf16_f32 v71, v66, v67
	global_store_dwordx4 v[146:147], v[68:71], off offset:256
	v_lshl_add_u64 v[146:147], v[146:147], 0, s[14:15]
	v_max_f32_e32 v56, 0, v56
	v_max_f32_e32 v57, 0, v57
	v_max_f32_e32 v58, 0, v58
	v_max_f32_e32 v59, 0, v59
	v_max_f32_e32 v60, 0, v60
	v_max_f32_e32 v61, 0, v61
	v_max_f32_e32 v62, 0, v62
	v_max_f32_e32 v63, 0, v63
	v_pk_mul_f32 v[56:57], v[56:57], v[56:57]
	v_pk_mul_f32 v[58:59], v[58:59], v[58:59]
	v_pk_mul_f32 v[60:61], v[60:61], v[60:61]
	v_pk_mul_f32 v[62:63], v[62:63], v[62:63]
	v_cvt_pk_bf16_f32 v60, v60, v61
	v_cvt_pk_bf16_f32 v61, v62, v63
	v_cvt_pk_bf16_f32 v62, v56, v57
	v_cvt_pk_bf16_f32 v63, v58, v59
	global_store_dwordx4 v[146:147], v[60:63], off
	v_max_f32_e32 v48, 0, v48
	v_max_f32_e32 v49, 0, v49
	v_max_f32_e32 v50, 0, v50
	v_max_f32_e32 v51, 0, v51
	v_max_f32_e32 v52, 0, v52
	v_max_f32_e32 v53, 0, v53
	v_max_f32_e32 v54, 0, v54
	v_max_f32_e32 v55, 0, v55
	v_pk_mul_f32 v[48:49], v[48:49], v[48:49]
	v_pk_mul_f32 v[50:51], v[50:51], v[50:51]
	v_pk_mul_f32 v[52:53], v[52:53], v[52:53]
	v_pk_mul_f32 v[54:55], v[54:55], v[54:55]
	v_cvt_pk_bf16_f32 v52, v52, v53
	v_cvt_pk_bf16_f32 v53, v54, v55
	v_cvt_pk_bf16_f32 v54, v48, v49
	v_cvt_pk_bf16_f32 v55, v50, v51
	global_store_dwordx4 v[146:147], v[52:55], off offset:256
	v_lshl_add_u64 v[146:147], v[146:147], 0, s[12:13]
	v_max_f32_e32 v40, 0, v40
	v_max_f32_e32 v41, 0, v41
	v_max_f32_e32 v42, 0, v42
	v_max_f32_e32 v43, 0, v43
	v_max_f32_e32 v44, 0, v44
	v_max_f32_e32 v45, 0, v45
	v_max_f32_e32 v46, 0, v46
	v_max_f32_e32 v47, 0, v47
	v_pk_mul_f32 v[40:41], v[40:41], v[40:41]
	v_pk_mul_f32 v[42:43], v[42:43], v[42:43]
	v_pk_mul_f32 v[44:45], v[44:45], v[44:45]
	v_pk_mul_f32 v[46:47], v[46:47], v[46:47]
	v_cvt_pk_bf16_f32 v44, v44, v45
	v_cvt_pk_bf16_f32 v45, v46, v47
	v_cvt_pk_bf16_f32 v46, v40, v41
	v_cvt_pk_bf16_f32 v47, v42, v43
	global_store_dwordx4 v[146:147], v[44:47], off
	v_max_f32_e32 v32, 0, v32
	v_max_f32_e32 v33, 0, v33
	v_max_f32_e32 v34, 0, v34
	v_max_f32_e32 v35, 0, v35
	v_max_f32_e32 v36, 0, v36
	v_max_f32_e32 v37, 0, v37
	v_max_f32_e32 v38, 0, v38
	v_max_f32_e32 v39, 0, v39
	v_pk_mul_f32 v[32:33], v[32:33], v[32:33]
	v_pk_mul_f32 v[34:35], v[34:35], v[34:35]
	v_pk_mul_f32 v[36:37], v[36:37], v[36:37]
	v_pk_mul_f32 v[38:39], v[38:39], v[38:39]
	v_cvt_pk_bf16_f32 v36, v36, v37
	v_cvt_pk_bf16_f32 v37, v38, v39
	v_cvt_pk_bf16_f32 v38, v32, v33
	v_cvt_pk_bf16_f32 v39, v34, v35
	global_store_dwordx4 v[146:147], v[36:39], off offset:256
	v_lshl_add_u64 v[146:147], v[146:147], 0, s[12:13]
	v_max_f32_e32 v24, 0, v24
	v_max_f32_e32 v25, 0, v25
	v_max_f32_e32 v26, 0, v26
	v_max_f32_e32 v27, 0, v27
	v_max_f32_e32 v28, 0, v28
	v_max_f32_e32 v29, 0, v29
	v_max_f32_e32 v30, 0, v30
	v_max_f32_e32 v31, 0, v31
	v_pk_mul_f32 v[24:25], v[24:25], v[24:25]
	v_pk_mul_f32 v[26:27], v[26:27], v[26:27]
	v_pk_mul_f32 v[28:29], v[28:29], v[28:29]
	v_pk_mul_f32 v[30:31], v[30:31], v[30:31]
	v_cvt_pk_bf16_f32 v28, v28, v29
	v_cvt_pk_bf16_f32 v29, v30, v31
	v_cvt_pk_bf16_f32 v30, v24, v25
	v_cvt_pk_bf16_f32 v31, v26, v27
	global_store_dwordx4 v[146:147], v[28:31], off
	v_max_f32_e32 v16, 0, v16
	v_max_f32_e32 v17, 0, v17
	v_max_f32_e32 v18, 0, v18
	v_max_f32_e32 v19, 0, v19
	v_max_f32_e32 v20, 0, v20
	v_max_f32_e32 v21, 0, v21
	v_max_f32_e32 v22, 0, v22
	v_max_f32_e32 v23, 0, v23
	v_pk_mul_f32 v[16:17], v[16:17], v[16:17]
	v_pk_mul_f32 v[18:19], v[18:19], v[18:19]
	v_pk_mul_f32 v[20:21], v[20:21], v[20:21]
	v_pk_mul_f32 v[22:23], v[22:23], v[22:23]
	v_cvt_pk_bf16_f32 v20, v20, v21
	v_cvt_pk_bf16_f32 v21, v22, v23
	v_cvt_pk_bf16_f32 v22, v16, v17
	v_cvt_pk_bf16_f32 v23, v18, v19
	global_store_dwordx4 v[146:147], v[20:23], off offset:256
	v_lshl_add_u64 v[146:147], v[146:147], 0, s[12:13]
	v_max_f32_e32 v8, 0, v8
	v_max_f32_e32 v9, 0, v9
	v_max_f32_e32 v10, 0, v10
	v_max_f32_e32 v11, 0, v11
	v_max_f32_e32 v12, 0, v12
	v_max_f32_e32 v13, 0, v13
	v_max_f32_e32 v14, 0, v14
	v_max_f32_e32 v15, 0, v15
	v_pk_mul_f32 v[8:9], v[8:9], v[8:9]
	v_pk_mul_f32 v[10:11], v[10:11], v[10:11]
	v_pk_mul_f32 v[12:13], v[12:13], v[12:13]
	v_pk_mul_f32 v[14:15], v[14:15], v[14:15]
	v_cvt_pk_bf16_f32 v12, v12, v13
	v_cvt_pk_bf16_f32 v13, v14, v15
	v_cvt_pk_bf16_f32 v14, v8, v9
	v_cvt_pk_bf16_f32 v15, v10, v11
	global_store_dwordx4 v[146:147], v[12:15], off
	v_max_f32_e32 v0, 0, v0
	v_max_f32_e32 v1, 0, v1
	v_max_f32_e32 v2, 0, v2
	v_max_f32_e32 v3, 0, v3
	v_max_f32_e32 v4, 0, v4
	v_max_f32_e32 v5, 0, v5
	v_max_f32_e32 v6, 0, v6
	v_max_f32_e32 v7, 0, v7
	v_pk_mul_f32 v[0:1], v[0:1], v[0:1]
	v_pk_mul_f32 v[2:3], v[2:3], v[2:3]
	v_pk_mul_f32 v[4:5], v[4:5], v[4:5]
	v_pk_mul_f32 v[6:7], v[6:7], v[6:7]
	v_cvt_pk_bf16_f32 v4, v4, v5
	v_cvt_pk_bf16_f32 v5, v6, v7
	v_cvt_pk_bf16_f32 v6, v0, v1
	v_cvt_pk_bf16_f32 v7, v2, v3
	global_store_dwordx4 v[146:147], v[4:7], off offset:256
	v_readlane_b32 s68, v255, 34
	v_readlane_b32 s69, v255, 35
	s_andn2_b64 vcc, exec, s[38:39]
	s_mov_b64 s[38:39], -1
	s_cbranch_vccnz .LBB0_902
	s_andn2_b64 vcc, exec, s[36:37]
	s_cbranch_vccnz .LBB0_901
	s_barrier
	s_branch .LBB0_901
